# speedup vs baseline: 1.0602x; 1.0015x over previous
; template <int MODE>
; __device__ __forceinline__ void attn_unit(LAS unsigned char* lds, const bf16_t* __restrict__ qkvz, bf16_t* __restrict__ A2, const int b, const int hd, const int qb, const AttnX& X, const int tid) {
;     ...
;                     if (t + 5 <= myc) { const float bc = tbl[512]; S0 = S0 * c2 + bc; S1 = S1 * c2 + bc; }
;                     else {
;                         const int relb = (q0w + r32) - t * 64 - 4 * hh + 256;
;                         f32x16 B0, B1;
; #pragma unroll
;                         for (int i = 0; i < 16; ++i) { const int kofs = (i & 3) + 8 * (i >> 2);
;                             int i0 = relb - kofs, i1 = relb - kofs - 32;
;                             i0 = i0 < 0 ? 0 : (i0 > 512 ? 512 : i0); i1 = i1 < 0 ? 0 : (i1 > 512 ? 512 : i1);
;                             B0[i] = tbl[i0]; B1[i] = tbl[i1]; }
;                         S0 = S0 * c2 + B0; S1 = S1 * c2 + B1;
.LBB0_617:
	s_andn2_b64 vcc, exec, s[12:13]
	v_mov_b32_e32 v84, v80
	v_mov_b32_e32 v85, v80
	v_mov_b32_e32 v86, v80
	v_mov_b32_e32 v87, v80
	v_mov_b32_e32 v88, v80
	v_mov_b32_e32 v89, v80
	v_mov_b32_e32 v90, v80
	v_mov_b32_e32 v91, v80
	v_mov_b32_e32 v92, v80
	v_mov_b32_e32 v93, v80
	v_mov_b32_e32 v94, v80
	v_mov_b32_e32 v95, v80
	v_mov_b32_e32 v96, v80
	v_mov_b32_e32 v97, v80
	s_cbranch_vccnz .LBB0_619
	v_add_u32_e32 v64, -32, v147
	v_cmp_lt_u32_e32 vcc, 0x1c5, v64
	s_cbranch_vccnz .Lbd_bias_slow
	v_lshlrev_b32_e32 v149, 2, v147
	ds_read_b32 v64, v149 offset:43116
	ds_read_b32 v82, v149 offset:42988
	ds_read_b32 v65, v149 offset:43112
	ds_read_b32 v80, v149 offset:42984
	ds_read_b32 v66, v149 offset:43108
	ds_read_b32 v84, v149 offset:42980
	ds_read_b32 v67, v149 offset:43104
	ds_read_b32 v85, v149 offset:42976
	ds_read_b32 v68, v149 offset:43084
	ds_read_b32 v86, v149 offset:42956
	ds_read_b32 v69, v149 offset:43080
	ds_read_b32 v87, v149 offset:42952
	ds_read_b32 v70, v149 offset:43076
	ds_read_b32 v88, v149 offset:42948
	ds_read_b32 v71, v149 offset:43072
	ds_read_b32 v89, v149 offset:42944
	ds_read_b32 v72, v149 offset:43052
	ds_read_b32 v90, v149 offset:42924
	ds_read_b32 v73, v149 offset:43048
	ds_read_b32 v91, v149 offset:42920
	ds_read_b32 v74, v149 offset:43044
	ds_read_b32 v92, v149 offset:42916
	ds_read_b32 v75, v149 offset:43040
	ds_read_b32 v93, v149 offset:42912
	ds_read_b32 v76, v149 offset:43020
	ds_read_b32 v94, v149 offset:42892
	ds_read_b32 v78, v149 offset:43012
	ds_read_b32 v79, v149 offset:43008
	ds_read_b32 v77, v149 offset:43016
	ds_read_b32 v95, v149 offset:42888
	ds_read_b32 v96, v149 offset:42884
	ds_read_b32 v97, v149 offset:42880
	s_branch .Lbd_bias_join
.Lbd_bias_slow:
	v_add_u32_e32 v64, 27, v147
	v_med3_i32 v65, v64, 0, v144
	v_med3_i32 v64, v64, 32, v145
	v_lshl_add_u32 v66, v64, 2, 0
	v_add_u32_e32 v64, 26, v147
	v_med3_i32 v67, v64, 0, v144
	v_med3_i32 v64, v64, 32, v145
	v_lshl_add_u32 v68, v64, 2, 0
	v_add_u32_e32 v64, 25, v147
	v_med3_i32 v69, v64, 0, v144
	v_med3_i32 v64, v64, 32, v145
	v_lshl_add_u32 v70, v64, 2, 0
	v_add_u32_e32 v64, 24, v147
	v_lshl_add_u32 v65, v65, 2, 0
	v_lshl_add_u32 v67, v67, 2, 0
	v_med3_i32 v71, v64, 0, v144
	v_med3_i32 v64, v64, 32, v145
	v_lshl_add_u32 v69, v69, 2, 0
	v_lshl_add_u32 v71, v71, 2, 0
	v_lshl_add_u32 v72, v64, 2, 0
	ds_read_b32 v64, v65 offset:43008
	ds_read_b32 v82, v66 offset:42880
	ds_read_b32 v65, v67 offset:43008
	ds_read_b32 v80, v68 offset:42880
	ds_read_b32 v66, v69 offset:43008
	ds_read_b32 v84, v70 offset:42880
	ds_read_b32 v67, v71 offset:43008
	ds_read_b32 v85, v72 offset:42880
	v_add_u32_e32 v68, 19, v147
	v_med3_i32 v69, v68, 0, v144
	v_med3_i32 v68, v68, 32, v145
	v_lshl_add_u32 v70, v68, 2, 0
	v_add_u32_e32 v68, 18, v147
	v_med3_i32 v71, v68, 0, v144
	v_med3_i32 v68, v68, 32, v145
	v_lshl_add_u32 v72, v68, 2, 0
	v_add_u32_e32 v68, 17, v147
	v_med3_i32 v73, v68, 0, v144
	v_med3_i32 v68, v68, 32, v145
	v_lshl_add_u32 v74, v68, 2, 0
	v_add_u32_e32 v68, 16, v147
	v_lshl_add_u32 v69, v69, 2, 0
	v_lshl_add_u32 v71, v71, 2, 0
	v_med3_i32 v75, v68, 0, v144
	v_med3_i32 v68, v68, 32, v145
	v_lshl_add_u32 v73, v73, 2, 0
	v_lshl_add_u32 v75, v75, 2, 0
	v_lshl_add_u32 v76, v68, 2, 0
	ds_read_b32 v68, v69 offset:43008
	ds_read_b32 v86, v70 offset:42880
	ds_read_b32 v69, v71 offset:43008
	ds_read_b32 v87, v72 offset:42880
	ds_read_b32 v70, v73 offset:43008
	ds_read_b32 v88, v74 offset:42880
	ds_read_b32 v71, v75 offset:43008
	ds_read_b32 v89, v76 offset:42880
	v_add_u32_e32 v72, 11, v147
	v_med3_i32 v73, v72, 0, v144
	v_med3_i32 v72, v72, 32, v145
	v_lshl_add_u32 v74, v72, 2, 0
	v_add_u32_e32 v72, 10, v147
	v_med3_i32 v75, v72, 0, v144
	v_med3_i32 v72, v72, 32, v145
	v_lshl_add_u32 v76, v72, 2, 0
	v_add_u32_e32 v72, 9, v147
	v_med3_i32 v77, v72, 0, v144
	v_med3_i32 v72, v72, 32, v145
	v_lshl_add_u32 v78, v72, 2, 0
	v_add_u32_e32 v72, 8, v147
	v_lshl_add_u32 v73, v73, 2, 0
	v_lshl_add_u32 v75, v75, 2, 0
	v_med3_i32 v79, v72, 0, v144
	v_med3_i32 v72, v72, 32, v145
	v_lshl_add_u32 v77, v77, 2, 0
	v_lshl_add_u32 v79, v79, 2, 0
	v_lshl_add_u32 v83, v72, 2, 0
	ds_read_b32 v72, v73 offset:43008
	ds_read_b32 v90, v74 offset:42880
	ds_read_b32 v73, v75 offset:43008
	ds_read_b32 v91, v76 offset:42880
	ds_read_b32 v74, v77 offset:43008
	ds_read_b32 v92, v78 offset:42880
	ds_read_b32 v75, v79 offset:43008
	ds_read_b32 v93, v83 offset:42880
	v_add_u32_e32 v76, 3, v147
	v_med3_i32 v77, v76, 0, v144
	v_med3_i32 v76, v76, 32, v145
	v_lshl_add_u32 v78, v76, 2, 0
	v_add_u32_e32 v76, 2, v147
	v_med3_i32 v79, v76, 0, v144
	v_med3_i32 v76, v76, 32, v145
	v_lshl_add_u32 v95, v76, 2, 0
	v_add_u32_e32 v76, 1, v147
	v_lshl_add_u32 v83, v79, 2, 0
	v_med3_i32 v79, v76, 0, v144
	v_med3_i32 v76, v76, 32, v145
	v_lshl_add_u32 v96, v76, 2, 0
	v_med3_i32 v76, v147, 0, v144
	v_lshl_add_u32 v77, v77, 2, 0
	v_lshl_add_u32 v79, v79, 2, 0
	v_med3_i32 v94, v147, 32, v145
	v_lshl_add_u32 v97, v76, 2, 0
	v_lshl_add_u32 v149, v94, 2, 0
	ds_read_b32 v76, v77 offset:43008
	ds_read_b32 v94, v78 offset:42880
	ds_read_b32 v78, v79 offset:43008
	ds_read_b32 v79, v97 offset:43008
	ds_read_b32 v77, v83 offset:43008
	ds_read_b32 v95, v95 offset:42880
	ds_read_b32 v96, v96 offset:42880
	ds_read_b32 v97, v149 offset:42880
.Lbd_bias_join:
	s_waitcnt lgkmcnt(4)
	v_pk_fma_f32 v[78:79], v[62:63], s[24:25], v[78:79] op_sel_hi:[1,0,1]
	s_waitcnt lgkmcnt(3)
	v_pk_fma_f32 v[76:77], v[60:61], s[24:25], v[76:77] op_sel_hi:[1,0,1]
	v_pk_fma_f32 v[74:75], v[58:59], s[24:25], v[74:75] op_sel_hi:[1,0,1]
	v_pk_fma_f32 v[72:73], v[56:57], s[24:25], v[72:73] op_sel_hi:[1,0,1]
	v_pk_fma_f32 v[70:71], v[54:55], s[24:25], v[70:71] op_sel_hi:[1,0,1]
	v_pk_fma_f32 v[68:69], v[52:53], s[24:25], v[68:69] op_sel_hi:[1,0,1]
	v_pk_fma_f32 v[66:67], v[50:51], s[24:25], v[66:67] op_sel_hi:[1,0,1]
	v_pk_fma_f32 v[64:65], v[48:49], s[24:25], v[64:65] op_sel_hi:[1,0,1]
